# EpiUp row statistics cached per row panel and loaded in one round trip; attention K prefetch made a real prefetch; gMLP units assigned to the workgroups with the lighter attention share (256-workgroup
# baseline (speedup 1.0000x reference)
; #define LAS __attribute__((address_space(3)))
; __device__ __forceinline__ unsigned pk2(float lo, float hi) { f32x2 v = {lo, hi}; bf16x2_t b = __builtin_convertvector(v, bf16x2_t); return __builtin_bit_cast(unsigned, b); }
; __device__ __forceinline__ void gmlp_unit(const GmlpP& P, int b, int ch, LAS unsigned char* lds, int wave, int lane_in) {
;     ...
;     __syncthreads();
; #pragma unroll
;     for (int nt = 0; nt < 2; ++nt) {
;         const int t = 32 * (nt == 0 ? tt0 : tt1) + r32;
;         const float tot = (ssqg[t] + ssqg[128 + t]) + (ssqg[256 + t] + ssqg[384 + t]);
;         const float r = __builtin_amdgcn_rsqf(tot * (1.0f / GW) + EPS);
;         bf16_t* op = P.MIX + (tok0 + t) * DM + AW + gI * 128 + 4 * h;
; #pragma unroll
;         for (int mt = 0; mt < 4; ++mt)
; #pragma unroll
;             for (int e4 = 0; e4 < 4; ++e4) {
;                 const f32x4 gg = *(const LAS f32x4*)(lds + LDS_GG + (gI * 128 + 32 * mt + 8 * e4 + 4 * h) * 4);
;                 u32x2 w; w.x = pk2(acc[mt][nt][4 * e4] * r * gg[0], acc[mt][nt][4 * e4 + 1] * r * gg[1]); w.y = pk2(acc[mt][nt][4 * e4 + 2] * r * gg[2], acc[mt][nt][4 * e4 + 3] * r * gg[3]);
;                 *(u32x2*)(op + 32 * mt + 8 * e4) = w;
;             }
; __global__ void __launch_bounds__(512, 2) mk_fwd(Args args) {
;     ...
;         for (int a = bx; a < 256 * REP_GM; a += G) gmlp_unit(GP, (a & 255) >> 4, a & 15, lds, wave, lane);
.LBB0_535:
	s_add_u32 s0, s84, 0x1b00000
	v_readlane_b32 s4, v243, 24
	s_addc_u32 s1, s85, 0
	s_and_b32 s6, s4, 0xffffff80
	v_readlane_b32 s56, v243, 4
	s_ashr_i32 s7, s6, 31
	v_readlane_b32 s66, v243, 14
	v_readlane_b32 s67, v243, 15
	s_bfe_u32 s14, s4, 0x10006
	s_and_b32 s18, s4, 0xffffffc0
	s_lshl_b64 s[4:5], s[6:7], 2
	s_mov_b64 s[22:23], s[66:67]
	v_readlane_b32 s68, v243, 16
	v_readlane_b32 s69, v243, 17
	s_add_u32 s8, s22, s4
	s_mov_b64 s[24:25], s[68:69]
	s_addc_u32 s9, s23, s5
	s_add_u32 s10, s24, s4
	s_addc_u32 s11, s25, s5
	s_lshl_b32 s20, s14, 6
	s_lshl_b64 s[16:17], s[6:7], 1
	s_add_u32 s15, s84, s16
	s_addc_u32 s19, s85, s17
	s_add_u32 s12, s15, 0xe000000
	s_addc_u32 s13, s19, 0
	s_lshl_b32 s21, s14, 5
	s_xor_b32 s23, s21, 0x60
	s_or_b32 s22, s6, s21
	s_or_b32 s25, s23, s18
	s_add_u32 s14, s15, 0xc000000
	v_mov_b32_e32 v141, 0
	s_addc_u32 s15, s19, 0
	s_or_b32 s28, s18, 0x60
	s_or_b32 s29, s6, 32
	s_or_b32 s30, s18, 64
	s_xor_b32 s31, s21, 32
	v_readlane_b32 s18, v243, 20
	s_movk_i32 s4, 0x80
	v_lshlrev_b32_e32 v138, 4, v0
	v_mov_b32_e32 v139, v141
	v_readlane_b32 s19, v243, 21
	s_add_u32 s16, s18, s16
	v_readlane_b32 s86, v243, 28
	v_readlane_b32 s94, v243, 26
	v_cmp_gt_u32_e64 s[4:5], s4, v0
	v_lshl_add_u64 v[142:143], s[44:45], 0, v[138:139]
	s_addc_u32 s17, s19, s17
	s_lshl_b32 s38, s2, 7
	s_mov_b32 s39, 0
	s_mov_b32 s19, 0
	s_movk_i32 s44, 0x1000
	s_movk_i32 s45, 0x2000
	s_movk_i32 s48, 0x110
	s_brev_b32 s24, 60
	v_mov_b32_e32 v1, 0x358637bd
	s_mov_b32 s49, s2
	v_readlane_b32 s67, v243, 30
	v_readlane_b32 s87, v243, 29
	v_readlane_b32 s95, v243, 27
	v_readlane_b32 s57, v243, 5
	v_readlane_b32 s58, v243, 6
	v_readlane_b32 s59, v243, 7
	v_readlane_b32 s60, v243, 8
	v_readlane_b32 s61, v243, 9
	v_readlane_b32 s62, v243, 10
	v_readlane_b32 s63, v243, 11
	v_readlane_b32 s64, v243, 12
	v_readlane_b32 s65, v243, 13
	v_readlane_b32 s70, v243, 18
	v_readlane_b32 s71, v243, 19
	s_cmp_eq_u32 s3, 0x100
	s_cbranch_scc1 .Lgmlp_paired
	s_mov_b32 s100, s3
	s_lshl_b32 s39, s3, 7
	s_movk_i32 s101, 0xff
	s_branch .LBB0_537
.Lgmlp_paired:
	s_mov_b32 s100, 8
	s_movk_i32 s39, 0x400
	s_add_i32 s101, s2, 8
	s_bitcmp1_b32 s2, 3
	s_cbranch_scc1 .LBB0_545
	s_branch .LBB0_537
.LBB0_536:
	s_or_b64 exec, exec, s[26:27]
	s_add_i32 s18, 0, 0x22000
	v_lshl_add_u32 v4, v157, 2, s18
	s_waitcnt lgkmcnt(0)
	s_barrier
	ds_read2st64_b32 v[2:3], v4 offset1:2
	ds_read2st64_b32 v[4:5], v4 offset0:4 offset1:6
	v_add_u32_e32 v6, s28, v144
	s_add_i32 s26, 0, 0x22800
	v_lshl_add_u32 v153, v6, 2, s26
	s_waitcnt lgkmcnt(1)
	v_mov_b32_e32 v6, v2
	s_waitcnt lgkmcnt(0)
	v_mov_b32_e32 v7, v4
	v_mov_b32_e32 v4, v3
	v_pk_add_f32 v[2:3], v[6:7], v[4:5]
	v_lshlrev_b32_e32 v140, 11, v156
	v_add_f32_e32 v2, v2, v3
	v_fmamk_f32 v2, v2, 0x3b000000, v1
	v_add_u32_e32 v4, s6, v144
	v_rsq_f32_e32 v152, v2
	v_lshl_add_u64 v[2:3], s[16:17], 0, v[140:141]
	v_lshl_add_u32 v140, v4, 2, s26
	ds_read_b128 v[6:9], v140
	v_lshlrev_b64 v[150:151], 1, v[144:145]
	v_lshl_add_u64 v[154:155], v[2:3], 0, v[150:151]
	ds_read_b128 v[2:5], v140 offset:32
	v_pk_mul_f32 v[10:11], v[114:115], v[152:153] op_sel_hi:[1,0]
	v_pk_mul_f32 v[12:13], v[116:117], v[152:153] op_sel_hi:[1,0]
	s_waitcnt lgkmcnt(1)
	v_pk_mul_f32 v[10:11], v[6:7], v[10:11]
	v_pk_mul_f32 v[12:13], v[8:9], v[12:13]
	v_cvt_pk_bf16_f32 v10, v10, v11
	v_cvt_pk_bf16_f32 v11, v12, v13
	global_store_dwordx2 v[154:155], v[10:11], off offset:1024
	v_pk_mul_f32 v[10:11], v[118:119], v[152:153] op_sel_hi:[1,0]
	v_pk_mul_f32 v[118:119], v[122:123], v[152:153] op_sel_hi:[1,0]
	s_waitcnt lgkmcnt(0)
	v_pk_mul_f32 v[10:11], v[2:3], v[10:11]
	v_pk_mul_f32 v[120:121], v[120:121], v[152:153] op_sel_hi:[1,0]
	v_cvt_pk_bf16_f32 v114, v10, v11
	v_pk_mul_f32 v[10:11], v[130:131], v[152:153] op_sel_hi:[1,0]
	v_pk_mul_f32 v[98:99], v[98:99], v[152:153] op_sel_hi:[1,0]
	v_pk_mul_f32 v[116:117], v[4:5], v[10:11]
	ds_read_b128 v[10:13], v140 offset:64
	v_cvt_pk_bf16_f32 v115, v116, v117
	global_store_dwordx2 v[154:155], v[114:115], off offset:1040
	ds_read_b128 v[114:117], v140 offset:96
	v_pk_mul_f32 v[100:101], v[100:101], v[152:153] op_sel_hi:[1,0]
	s_waitcnt lgkmcnt(1)
	v_pk_mul_f32 v[118:119], v[10:11], v[118:119]
	v_pk_mul_f32 v[120:121], v[12:13], v[120:121]
	v_cvt_pk_bf16_f32 v118, v118, v119
	v_cvt_pk_bf16_f32 v119, v120, v121
	global_store_dwordx2 v[154:155], v[118:119], off offset:1056
	v_pk_mul_f32 v[118:119], v[124:125], v[152:153] op_sel_hi:[1,0]
	v_pk_mul_f32 v[104:105], v[104:105], v[152:153] op_sel_hi:[1,0]
	s_waitcnt lgkmcnt(0)
	v_pk_mul_f32 v[118:119], v[118:119], v[114:115]
	v_pk_mul_f32 v[82:83], v[82:83], v[152:153] op_sel_hi:[1,0]
	v_cvt_pk_bf16_f32 v122, v118, v119
	v_pk_mul_f32 v[118:119], v[126:127], v[152:153] op_sel_hi:[1,0]
	v_pk_mul_f32 v[84:85], v[84:85], v[152:153] op_sel_hi:[1,0]
	v_pk_mul_f32 v[124:125], v[118:119], v[116:117]
	v_add_u32_e32 v118, s29, v144
	v_lshl_add_u32 v130, v118, 2, s26
	ds_read_b128 v[118:121], v130
	v_cvt_pk_bf16_f32 v123, v124, v125
	global_store_dwordx2 v[154:155], v[122:123], off offset:1072
	ds_read_b128 v[122:125], v130 offset:32
	v_pk_mul_f32 v[88:89], v[88:89], v[152:153] op_sel_hi:[1,0]
	s_waitcnt lgkmcnt(1)
	v_pk_mul_f32 v[98:99], v[98:99], v[118:119]
	v_pk_mul_f32 v[100:101], v[100:101], v[120:121]
	v_cvt_pk_bf16_f32 v98, v98, v99
	v_cvt_pk_bf16_f32 v99, v100, v101
	global_store_dwordx2 v[154:155], v[98:99], off offset:1088
	v_pk_mul_f32 v[98:99], v[102:103], v[152:153] op_sel_hi:[1,0]
	v_pk_mul_f32 v[66:67], v[66:67], v[152:153] op_sel_hi:[1,0]
	s_waitcnt lgkmcnt(0)
; #define LAS __attribute__((address_space(3)))
; __device__ __forceinline__ unsigned pk2(float lo, float hi) { f32x2 v = {lo, hi}; bf16x2_t b = __builtin_convertvector(v, bf16x2_t); return __builtin_bit_cast(unsigned, b); }
; __device__ __forceinline__ void gmlp_unit(const GmlpP& P, int b, int ch, LAS unsigned char* lds, int wave, int lane_in) {
;     ...
;     for (int nt = 0; nt < 2; ++nt) {
;         const int t = 32 * (nt == 0 ? tt0 : tt1) + r32;
;         const float tot = (ssqg[t] + ssqg[128 + t]) + (ssqg[256 + t] + ssqg[384 + t]);
;         const float r = __builtin_amdgcn_rsqf(tot * (1.0f / GW) + EPS);
;         bf16_t* op = P.MIX + (tok0 + t) * DM + AW + gI * 128 + 4 * h;
; #pragma unroll
;         for (int mt = 0; mt < 4; ++mt)
; #pragma unroll
;             for (int e4 = 0; e4 < 4; ++e4) {
;                 const f32x4 gg = *(const LAS f32x4*)(lds + LDS_GG + (gI * 128 + 32 * mt + 8 * e4 + 4 * h) * 4);
;                 u32x2 w; w.x = pk2(acc[mt][nt][4 * e4] * r * gg[0], acc[mt][nt][4 * e4 + 1] * r * gg[1]); w.y = pk2(acc[mt][nt][4 * e4 + 2] * r * gg[2], acc[mt][nt][4 * e4 + 3] * r * gg[3]);
;                 *(u32x2*)(op + 32 * mt + 8 * e4) = w;
;             }
; __global__ void __launch_bounds__(512, 2) mk_fwd(Args args) {
;     ...
;         for (int a = bx; a < 256 * REP_GM; a += G) gmlp_unit(GP, (a & 255) >> 4, a & 15, lds, wave, lane);
	v_pk_mul_f32 v[98:99], v[98:99], v[122:123]
	v_pk_mul_f32 v[68:69], v[68:69], v[152:153] op_sel_hi:[1,0]
	v_cvt_pk_bf16_f32 v102, v98, v99
	v_pk_mul_f32 v[98:99], v[128:129], v[152:153] op_sel_hi:[1,0]
	v_pk_mul_f32 v[72:73], v[72:73], v[152:153] op_sel_hi:[1,0]
	v_pk_mul_f32 v[126:127], v[98:99], v[124:125]
	ds_read_b128 v[98:101], v130 offset:64
	v_cvt_pk_bf16_f32 v103, v126, v127
	ds_read_b128 v[126:129], v130 offset:96
	global_store_dwordx2 v[154:155], v[102:103], off offset:1104
	v_pk_mul_f32 v[102:103], v[106:107], v[152:153] op_sel_hi:[1,0]
	s_waitcnt lgkmcnt(1)
	v_pk_mul_f32 v[104:105], v[104:105], v[100:101]
	v_pk_mul_f32 v[102:103], v[102:103], v[98:99]
	v_lshlrev_b32_e32 v140, 11, v139
	v_cvt_pk_bf16_f32 v102, v102, v103
	v_cvt_pk_bf16_f32 v103, v104, v105
	global_store_dwordx2 v[154:155], v[102:103], off offset:1120
	v_pk_mul_f32 v[102:103], v[108:109], v[152:153] op_sel_hi:[1,0]
	s_add_i32 s49, s49, s100
	s_waitcnt lgkmcnt(0)
	v_pk_mul_f32 v[102:103], v[102:103], v[126:127]
	s_add_i32 s38, s38, s39
	v_cvt_pk_bf16_f32 v106, v102, v103
	v_pk_mul_f32 v[102:103], v[110:111], v[152:153] op_sel_hi:[1,0]
	s_cmp_gt_i32 s49, s101
	v_pk_mul_f32 v[108:109], v[102:103], v[128:129]
	v_add_u32_e32 v102, s30, v144
	v_lshl_add_u32 v130, v102, 2, s26
	ds_read_b128 v[102:105], v130
	v_cvt_pk_bf16_f32 v107, v108, v109
	global_store_dwordx2 v[154:155], v[106:107], off offset:1136
	ds_read_b128 v[106:109], v130 offset:32
	s_waitcnt lgkmcnt(1)
	v_pk_mul_f32 v[82:83], v[82:83], v[102:103]
	v_pk_mul_f32 v[84:85], v[84:85], v[104:105]
	v_cvt_pk_bf16_f32 v82, v82, v83
	v_cvt_pk_bf16_f32 v83, v84, v85
	global_store_dwordx2 v[154:155], v[82:83], off offset:1152
	v_pk_mul_f32 v[82:83], v[86:87], v[152:153] op_sel_hi:[1,0]
	s_waitcnt lgkmcnt(0)
	v_pk_mul_f32 v[82:83], v[82:83], v[106:107]
	s_nop 0
	v_cvt_pk_bf16_f32 v86, v82, v83
	v_pk_mul_f32 v[82:83], v[112:113], v[152:153] op_sel_hi:[1,0]
	s_nop 0
	v_pk_mul_f32 v[110:111], v[82:83], v[108:109]
	ds_read_b128 v[82:85], v130 offset:64
	v_cvt_pk_bf16_f32 v87, v110, v111
	ds_read_b128 v[110:113], v130 offset:96
	global_store_dwordx2 v[154:155], v[86:87], off offset:1168
	v_pk_mul_f32 v[86:87], v[90:91], v[152:153] op_sel_hi:[1,0]
	s_waitcnt lgkmcnt(1)
	v_pk_mul_f32 v[88:89], v[88:89], v[84:85]
	v_pk_mul_f32 v[86:87], v[86:87], v[82:83]
	s_nop 0
	v_cvt_pk_bf16_f32 v86, v86, v87
	v_cvt_pk_bf16_f32 v87, v88, v89
	global_store_dwordx2 v[154:155], v[86:87], off offset:1184
	v_pk_mul_f32 v[86:87], v[92:93], v[152:153] op_sel_hi:[1,0]
	s_waitcnt lgkmcnt(0)
	v_pk_mul_f32 v[86:87], v[86:87], v[110:111]
	s_nop 0
	v_cvt_pk_bf16_f32 v90, v86, v87
	v_pk_mul_f32 v[86:87], v[94:95], v[152:153] op_sel_hi:[1,0]
	s_nop 0
	v_pk_mul_f32 v[92:93], v[86:87], v[112:113]
	ds_read_b128 v[86:89], v153
	v_cvt_pk_bf16_f32 v91, v92, v93
	global_store_dwordx2 v[154:155], v[90:91], off offset:1200
	ds_read_b128 v[90:93], v153 offset:32
	s_waitcnt lgkmcnt(1)
	v_pk_mul_f32 v[66:67], v[66:67], v[86:87]
	v_pk_mul_f32 v[68:69], v[68:69], v[88:89]
	v_cvt_pk_bf16_f32 v66, v66, v67
	v_cvt_pk_bf16_f32 v67, v68, v69
	global_store_dwordx2 v[154:155], v[66:67], off offset:1216
	v_pk_mul_f32 v[66:67], v[70:71], v[152:153] op_sel_hi:[1,0]
	s_waitcnt lgkmcnt(0)
	v_pk_mul_f32 v[66:67], v[66:67], v[90:91]
	s_nop 0
	v_cvt_pk_bf16_f32 v70, v66, v67
	v_pk_mul_f32 v[66:67], v[96:97], v[152:153] op_sel_hi:[1,0]
	s_nop 0
	v_pk_mul_f32 v[94:95], v[66:67], v[92:93]
	ds_read_b128 v[66:69], v153 offset:64
	v_cvt_pk_bf16_f32 v71, v94, v95
	ds_read_b128 v[94:97], v153 offset:96
	global_store_dwordx2 v[154:155], v[70:71], off offset:1232
	v_pk_mul_f32 v[70:71], v[74:75], v[152:153] op_sel_hi:[1,0]
	s_waitcnt lgkmcnt(1)
	v_pk_mul_f32 v[72:73], v[72:73], v[68:69]
	v_pk_mul_f32 v[70:71], v[70:71], v[66:67]
	s_nop 0
	v_cvt_pk_bf16_f32 v70, v70, v71
	v_cvt_pk_bf16_f32 v71, v72, v73
	global_store_dwordx2 v[154:155], v[70:71], off offset:1248
	v_pk_mul_f32 v[70:71], v[76:77], v[152:153] op_sel_hi:[1,0]
	v_pk_mul_f32 v[72:73], v[78:79], v[152:153] op_sel_hi:[1,0]
	s_waitcnt lgkmcnt(0)
	v_pk_mul_f32 v[70:71], v[70:71], v[94:95]
	v_pk_mul_f32 v[72:73], v[72:73], v[96:97]
	v_cvt_pk_bf16_f32 v70, v70, v71
	v_lshl_add_u32 v71, v158, 2, s18
	ds_read2st64_b32 v[74:75], v71 offset1:2
	ds_read2st64_b32 v[76:77], v71 offset0:4 offset1:6
	v_cvt_pk_bf16_f32 v71, v72, v73
	global_store_dwordx2 v[154:155], v[70:71], off offset:1264
	v_lshl_add_u64 v[72:73], s[16:17], 0, v[140:141]
	s_waitcnt lgkmcnt(1)
	v_mov_b32_e32 v70, v74
	s_waitcnt lgkmcnt(0)
; #define LAS __attribute__((address_space(3)))
; __device__ __forceinline__ unsigned pk2(float lo, float hi) { f32x2 v = {lo, hi}; bf16x2_t b = __builtin_convertvector(v, bf16x2_t); return __builtin_bit_cast(unsigned, b); }
; __device__ __forceinline__ void gmlp_unit(const GmlpP& P, int b, int ch, LAS unsigned char* lds, int wave, int lane_in) {
;     ...
;     for (int nt = 0; nt < 2; ++nt) {
;         const int t = 32 * (nt == 0 ? tt0 : tt1) + r32;
;         const float tot = (ssqg[t] + ssqg[128 + t]) + (ssqg[256 + t] + ssqg[384 + t]);
;         const float r = __builtin_amdgcn_rsqf(tot * (1.0f / GW) + EPS);
;         bf16_t* op = P.MIX + (tok0 + t) * DM + AW + gI * 128 + 4 * h;
; #pragma unroll
;         for (int mt = 0; mt < 4; ++mt)
; #pragma unroll
;             for (int e4 = 0; e4 < 4; ++e4) {
;                 const f32x4 gg = *(const LAS f32x4*)(lds + LDS_GG + (gI * 128 + 32 * mt + 8 * e4 + 4 * h) * 4);
;                 u32x2 w; w.x = pk2(acc[mt][nt][4 * e4] * r * gg[0], acc[mt][nt][4 * e4 + 1] * r * gg[1]); w.y = pk2(acc[mt][nt][4 * e4 + 2] * r * gg[2], acc[mt][nt][4 * e4 + 3] * r * gg[3]);
;                 *(u32x2*)(op + 32 * mt + 8 * e4) = w;
;             }
	v_mov_b32_e32 v71, v76
	v_mov_b32_e32 v76, v75
	v_pk_add_f32 v[70:71], v[70:71], v[76:77]
	v_lshl_add_u64 v[72:73], v[72:73], 0, v[150:151]
	v_add_f32_e32 v70, v70, v71
	v_fmamk_f32 v70, v70, 0x3b000000, v1
	v_rsq_f32_e32 v70, v70
	s_nop 0
	v_pk_mul_f32 v[64:65], v[64:65], v[70:71] op_sel_hi:[1,0]
	v_pk_mul_f32 v[62:63], v[62:63], v[70:71] op_sel_hi:[1,0]
	v_pk_mul_f32 v[6:7], v[6:7], v[64:65]
	v_pk_mul_f32 v[8:9], v[8:9], v[62:63]
	v_cvt_pk_bf16_f32 v6, v6, v7
	v_cvt_pk_bf16_f32 v7, v8, v9
	global_store_dwordx2 v[72:73], v[6:7], off offset:1024
	v_pk_mul_f32 v[6:7], v[60:61], v[70:71] op_sel_hi:[1,0]
	s_nop 0
	v_pk_mul_f32 v[2:3], v[2:3], v[6:7]
	v_pk_mul_f32 v[6:7], v[58:59], v[70:71] op_sel_hi:[1,0]
	v_cvt_pk_bf16_f32 v2, v2, v3
	v_pk_mul_f32 v[4:5], v[4:5], v[6:7]
	s_nop 0
	v_cvt_pk_bf16_f32 v3, v4, v5
	global_store_dwordx2 v[72:73], v[2:3], off offset:1040
	v_pk_mul_f32 v[2:3], v[56:57], v[70:71] op_sel_hi:[1,0]
	v_pk_mul_f32 v[4:5], v[54:55], v[70:71] op_sel_hi:[1,0]
	v_pk_mul_f32 v[2:3], v[10:11], v[2:3]
	v_pk_mul_f32 v[4:5], v[12:13], v[4:5]
	v_cvt_pk_bf16_f32 v2, v2, v3
	v_cvt_pk_bf16_f32 v3, v4, v5
	global_store_dwordx2 v[72:73], v[2:3], off offset:1056
	v_pk_mul_f32 v[2:3], v[52:53], v[70:71] op_sel_hi:[1,0]
	v_pk_mul_f32 v[4:5], v[50:51], v[70:71] op_sel_hi:[1,0]
	v_pk_mul_f32 v[2:3], v[114:115], v[2:3]
	v_pk_mul_f32 v[4:5], v[116:117], v[4:5]
	v_cvt_pk_bf16_f32 v2, v2, v3
	v_cvt_pk_bf16_f32 v3, v4, v5
	global_store_dwordx2 v[72:73], v[2:3], off offset:1072
	v_pk_mul_f32 v[2:3], v[36:37], v[70:71] op_sel_hi:[1,0]
	v_pk_mul_f32 v[4:5], v[34:35], v[70:71] op_sel_hi:[1,0]
	v_pk_mul_f32 v[2:3], v[118:119], v[2:3]
	v_pk_mul_f32 v[4:5], v[120:121], v[4:5]
	v_cvt_pk_bf16_f32 v2, v2, v3
	v_cvt_pk_bf16_f32 v3, v4, v5
	global_store_dwordx2 v[72:73], v[2:3], off offset:1088
	v_pk_mul_f32 v[2:3], v[38:39], v[70:71] op_sel_hi:[1,0]
	v_pk_mul_f32 v[4:5], v[40:41], v[70:71] op_sel_hi:[1,0]
	v_pk_mul_f32 v[2:3], v[122:123], v[2:3]
	v_pk_mul_f32 v[4:5], v[124:125], v[4:5]
	v_cvt_pk_bf16_f32 v2, v2, v3
	v_cvt_pk_bf16_f32 v3, v4, v5
	global_store_dwordx2 v[72:73], v[2:3], off offset:1104
	v_pk_mul_f32 v[2:3], v[42:43], v[70:71] op_sel_hi:[1,0]
	v_pk_mul_f32 v[4:5], v[44:45], v[70:71] op_sel_hi:[1,0]
	v_pk_mul_f32 v[2:3], v[98:99], v[2:3]
	v_pk_mul_f32 v[4:5], v[100:101], v[4:5]
	v_cvt_pk_bf16_f32 v2, v2, v3
	v_cvt_pk_bf16_f32 v3, v4, v5
	global_store_dwordx2 v[72:73], v[2:3], off offset:1120
	v_pk_mul_f32 v[2:3], v[46:47], v[70:71] op_sel_hi:[1,0]
	v_pk_mul_f32 v[4:5], v[48:49], v[70:71] op_sel_hi:[1,0]
	v_pk_mul_f32 v[2:3], v[126:127], v[2:3]
	v_pk_mul_f32 v[4:5], v[128:129], v[4:5]
	v_cvt_pk_bf16_f32 v2, v2, v3
	v_cvt_pk_bf16_f32 v3, v4, v5
	global_store_dwordx2 v[72:73], v[2:3], off offset:1136
	v_pk_mul_f32 v[2:3], v[18:19], v[70:71] op_sel_hi:[1,0]
	v_pk_mul_f32 v[4:5], v[20:21], v[70:71] op_sel_hi:[1,0]
	v_pk_mul_f32 v[2:3], v[102:103], v[2:3]
	v_pk_mul_f32 v[4:5], v[104:105], v[4:5]
	v_cvt_pk_bf16_f32 v2, v2, v3
	v_cvt_pk_bf16_f32 v3, v4, v5
	global_store_dwordx2 v[72:73], v[2:3], off offset:1152
	v_pk_mul_f32 v[2:3], v[22:23], v[70:71] op_sel_hi:[1,0]
	v_pk_mul_f32 v[4:5], v[24:25], v[70:71] op_sel_hi:[1,0]
	v_pk_mul_f32 v[2:3], v[106:107], v[2:3]
	v_pk_mul_f32 v[4:5], v[108:109], v[4:5]
	v_cvt_pk_bf16_f32 v2, v2, v3
	v_cvt_pk_bf16_f32 v3, v4, v5
	global_store_dwordx2 v[72:73], v[2:3], off offset:1168
	v_pk_mul_f32 v[2:3], v[26:27], v[70:71] op_sel_hi:[1,0]
	v_pk_mul_f32 v[4:5], v[28:29], v[70:71] op_sel_hi:[1,0]
	v_pk_mul_f32 v[2:3], v[82:83], v[2:3]
	v_pk_mul_f32 v[4:5], v[84:85], v[4:5]
	v_cvt_pk_bf16_f32 v2, v2, v3
	v_cvt_pk_bf16_f32 v3, v4, v5
	global_store_dwordx2 v[72:73], v[2:3], off offset:1184
	v_pk_mul_f32 v[2:3], v[30:31], v[70:71] op_sel_hi:[1,0]
	v_pk_mul_f32 v[4:5], v[32:33], v[70:71] op_sel_hi:[1,0]
	v_pk_mul_f32 v[2:3], v[110:111], v[2:3]
	v_pk_mul_f32 v[4:5], v[112:113], v[4:5]
	v_cvt_pk_bf16_f32 v2, v2, v3
	v_cvt_pk_bf16_f32 v3, v4, v5
	global_store_dwordx2 v[72:73], v[2:3], off offset:1200
	v_pk_mul_f32 v[2:3], v[80:81], v[70:71] op_sel_hi:[1,0]
	v_pk_mul_f32 v[4:5], v[132:133], v[70:71] op_sel_hi:[1,0]
	v_pk_mul_f32 v[2:3], v[86:87], v[2:3]
	v_pk_mul_f32 v[4:5], v[88:89], v[4:5]
	v_cvt_pk_bf16_f32 v2, v2, v3
	v_cvt_pk_bf16_f32 v3, v4, v5
	global_store_dwordx2 v[72:73], v[2:3], off offset:1216
	v_pk_mul_f32 v[2:3], v[134:135], v[70:71] op_sel_hi:[1,0]
	v_pk_mul_f32 v[4:5], v[136:137], v[70:71] op_sel_hi:[1,0]
	v_pk_mul_f32 v[2:3], v[90:91], v[2:3]
	v_pk_mul_f32 v[4:5], v[92:93], v[4:5]
	v_cvt_pk_bf16_f32 v2, v2, v3
	v_cvt_pk_bf16_f32 v3, v4, v5
	global_store_dwordx2 v[72:73], v[2:3], off offset:1232
	v_pk_mul_f32 v[2:3], v[146:147], v[70:71] op_sel_hi:[1,0]
	v_pk_mul_f32 v[4:5], v[148:149], v[70:71] op_sel_hi:[1,0]
	v_pk_mul_f32 v[2:3], v[66:67], v[2:3]
	v_pk_mul_f32 v[4:5], v[68:69], v[4:5]
	v_cvt_pk_bf16_f32 v2, v2, v3
	v_cvt_pk_bf16_f32 v3, v4, v5
	global_store_dwordx2 v[72:73], v[2:3], off offset:1248
	v_pk_mul_f32 v[2:3], v[14:15], v[70:71] op_sel_hi:[1,0]
	v_pk_mul_f32 v[4:5], v[16:17], v[70:71] op_sel_hi:[1,0]
	v_pk_mul_f32 v[2:3], v[94:95], v[2:3]
	v_pk_mul_f32 v[4:5], v[96:97], v[4:5]
	v_cvt_pk_bf16_f32 v2, v2, v3
	v_cvt_pk_bf16_f32 v3, v4, v5
	global_store_dwordx2 v[72:73], v[2:3], off offset:1264
	s_cbranch_scc1 .LBB0_545
